# merge gate epilogue: six second-half branch-tile loads issued at the top of the epilogue into the (already copied-out) parking registers
# baseline (speedup 1.0000x reference)
.LBB0_1076:
	s_waitcnt vmcnt(0)
	v_mov_b32_e32 v190, v222
	v_mov_b32_e32 v191, v223
	v_mov_b32_e32 v192, v233
	v_mov_b32_e32 v193, v234
	v_mov_b32_e32 v182, v235
	v_mov_b32_e32 v183, v238
	v_mov_b32_e32 v184, v242
	v_mov_b32_e32 v185, v243
	v_mov_b32_e32 v174, v244
	v_mov_b32_e32 v175, v245
	v_mov_b32_e32 v176, v246
	v_mov_b32_e32 v177, v247
	v_mov_b32_e32 v166, v248
	v_mov_b32_e32 v167, v249
	v_mov_b32_e32 v168, v250
	v_mov_b32_e32 v169, v251
	v_mov_b32_e32 v158, v194
	v_mov_b32_e32 v159, v195
	v_mov_b32_e32 v160, v196
	v_mov_b32_e32 v161, v197
	v_mov_b32_e32 v150, v225
	v_mov_b32_e32 v151, v226
	v_mov_b32_e32 v152, v227
	v_mov_b32_e32 v153, v228
	v_mov_b32_e32 v142, v229
	v_mov_b32_e32 v143, v230
	v_mov_b32_e32 v144, v231
	v_mov_b32_e32 v145, v232
	v_mov_b32_e32 v134, v236
	v_mov_b32_e32 v135, v237
	v_mov_b32_e32 v136, v239
	v_mov_b32_e32 v137, v240
	v_mov_b32_e32 v223, 0
	v_mov_b32_e32 v222, 0x10000
	v_lshl_add_u64 v[250:251], v[208:209], 0, v[222:223]
	global_load_dwordx4 v[194:197], v[250:251], off
	global_load_dwordx4 v[226:229], v[250:251], off offset:256
	v_mov_b32_e32 v222, 0x12000
	v_lshl_add_u64 v[250:251], v[208:209], 0, v[222:223]
	global_load_dwordx4 v[230:233], v[250:251], off
	global_load_dwordx4 v[234:237], v[250:251], off offset:256
	v_mov_b32_e32 v222, 0x14000
	v_lshl_add_u64 v[250:251], v[208:209], 0, v[222:223]
	global_load_dwordx4 v[242:245], v[250:251], off
	global_load_dwordx4 v[246:249], v[250:251], off offset:256
	v_lshlrev_b32_e32 v212, 16, v190
	v_and_b32_e32 v213, 0xffff0000, v190
	v_mul_f32_e32 v190, 0xbfb8aa3b, v126
	v_exp_f32_e32 v218, v190
	v_mul_f32_e32 v190, 0xbfb8aa3b, v127
	v_exp_f32_e32 v219, v190
	s_lshl_b32 s56, s24, 5
	v_pk_add_f32 v[218:219], v[218:219], 1.0 op_sel_hi:[1,0]
	s_nop 0
	s_nop 0
	v_rcp_f32_e32 v219, v219
	s_nop 0
	s_nop 0
	v_rcp_f32_e32 v218, v218
	s_nop 0
	v_lshlrev_b32_e32 v220, 16, v186
	v_and_b32_e32 v221, 0xffff0000, v186
	v_mul_f32_e32 v186, 0xbfb8aa3b, v128
	v_pk_fma_f32 v[212:213], v[218:219], v[212:213], v[220:221]
	v_exp_f32_e32 v218, v186
	v_mul_f32_e32 v186, 0xbfb8aa3b, v129
	v_exp_f32_e32 v219, v186
	v_lshlrev_b32_e32 v190, 16, v191
	v_and_b32_e32 v191, 0xffff0000, v191
	v_pk_add_f32 v[218:219], v[218:219], 1.0 op_sel_hi:[1,0]
	s_nop 0
	s_nop 0
	v_rcp_f32_e32 v219, v219
	s_nop 0
	s_nop 0
	v_rcp_f32_e32 v218, v218
	s_nop 0
	v_lshlrev_b32_e32 v186, 16, v187
	v_and_b32_e32 v187, 0xffff0000, v187
	v_pk_fma_f32 v[190:191], v[218:219], v[190:191], v[186:187]
	v_lshlrev_b32_e32 v186, 16, v192
	v_and_b32_e32 v187, 0xffff0000, v192
	v_mul_f32_e32 v192, 0xbfb8aa3b, v122
	v_exp_f32_e32 v218, v192
	v_mul_f32_e32 v192, 0xbfb8aa3b, v123
	v_exp_f32_e32 v219, v192
	s_nop 0
	v_pk_add_f32 v[218:219], v[218:219], 1.0 op_sel_hi:[1,0]
	s_nop 0
	s_nop 0
	v_rcp_f32_e32 v219, v219
	s_nop 0
	s_nop 0
	v_lshlrev_b32_e32 v220, 16, v188
	v_and_b32_e32 v221, 0xffff0000, v188
	v_mul_f32_e32 v188, 0xbfb8aa3b, v124
	v_rcp_f32_e32 v218, v218
	s_nop 0
	v_exp_f32_e32 v192, v188
	v_mul_f32_e32 v188, 0xbfb8aa3b, v125
	v_pk_fma_f32 v[218:219], v[218:219], v[186:187], v[220:221]
	v_lshlrev_b32_e32 v186, 16, v193
	v_and_b32_e32 v187, 0xffff0000, v193
	v_exp_f32_e32 v193, v188
	s_nop 0
	v_pk_add_f32 v[192:193], v[192:193], 1.0 op_sel_hi:[1,0]
	s_nop 0
	s_nop 0
	v_rcp_f32_e32 v193, v193
	s_nop 0
	s_nop 0
	v_rcp_f32_e32 v192, v192
	s_nop 0
	v_lshlrev_b32_e32 v188, 16, v189
	v_and_b32_e32 v189, 0xffff0000, v189
	v_pk_fma_f32 v[192:193], v[192:193], v[186:187], v[188:189]
	v_cvt_pk_bf16_f32 v186, v212, v213
	v_cvt_pk_bf16_f32 v187, v190, v191
	v_cvt_pk_bf16_f32 v188, v218, v219
	v_cvt_pk_bf16_f32 v189, v192, v193
	global_store_dwordx4 v[210:211], v[186:189], off
	s_nop 1
	v_lshlrev_b32_e32 v186, 16, v182
	v_and_b32_e32 v187, 0xffff0000, v182
	v_mul_f32_e32 v182, 0xbfb8aa3b, v110
	v_exp_f32_e32 v188, v182
	v_mul_f32_e32 v182, 0xbfb8aa3b, v111
	v_exp_f32_e32 v189, v182
	s_nop 0
	v_pk_add_f32 v[188:189], v[188:189], 1.0 op_sel_hi:[1,0]
	s_nop 0
	s_nop 0
	v_rcp_f32_e32 v189, v189
	s_nop 0
	s_nop 0
	v_rcp_f32_e32 v188, v188
	s_nop 0
	v_lshlrev_b32_e32 v190, 16, v178
	v_and_b32_e32 v191, 0xffff0000, v178
	v_mul_f32_e32 v178, 0xbfb8aa3b, v112
	v_pk_fma_f32 v[186:187], v[188:189], v[186:187], v[190:191]
	v_exp_f32_e32 v188, v178
	v_mul_f32_e32 v178, 0xbfb8aa3b, v113
	v_exp_f32_e32 v189, v178
	v_lshlrev_b32_e32 v182, 16, v183
	v_and_b32_e32 v183, 0xffff0000, v183
	v_pk_add_f32 v[188:189], v[188:189], 1.0 op_sel_hi:[1,0]
	s_nop 0
	s_nop 0
	v_rcp_f32_e32 v189, v189
	s_nop 0
	s_nop 0
	v_rcp_f32_e32 v188, v188
	s_nop 0
	v_lshlrev_b32_e32 v178, 16, v179
	v_and_b32_e32 v179, 0xffff0000, v179
	v_pk_fma_f32 v[182:183], v[188:189], v[182:183], v[178:179]
	v_lshlrev_b32_e32 v178, 16, v184
	v_and_b32_e32 v179, 0xffff0000, v184
	v_mul_f32_e32 v184, 0xbfb8aa3b, v106
	v_exp_f32_e32 v188, v184
	v_mul_f32_e32 v184, 0xbfb8aa3b, v107
	v_exp_f32_e32 v189, v184
	s_nop 0
	v_pk_add_f32 v[188:189], v[188:189], 1.0 op_sel_hi:[1,0]
	s_nop 0
	s_nop 0
	v_rcp_f32_e32 v189, v189
	s_nop 0
	s_nop 0
	v_lshlrev_b32_e32 v190, 16, v180
	v_and_b32_e32 v191, 0xffff0000, v180
	v_mul_f32_e32 v180, 0xbfb8aa3b, v108
	v_rcp_f32_e32 v188, v188
	s_nop 0
	v_exp_f32_e32 v184, v180
	v_mul_f32_e32 v180, 0xbfb8aa3b, v109
	v_pk_fma_f32 v[188:189], v[188:189], v[178:179], v[190:191]
	v_lshlrev_b32_e32 v178, 16, v185
	v_and_b32_e32 v179, 0xffff0000, v185
	v_exp_f32_e32 v185, v180
	s_nop 0
	v_pk_add_f32 v[184:185], v[184:185], 1.0 op_sel_hi:[1,0]
	s_nop 0
	s_nop 0
	v_rcp_f32_e32 v185, v185
	s_nop 0
	s_nop 0
	v_rcp_f32_e32 v184, v184
	s_nop 0
	v_lshlrev_b32_e32 v180, 16, v181
	v_and_b32_e32 v181, 0xffff0000, v181
	v_pk_fma_f32 v[184:185], v[184:185], v[178:179], v[180:181]
	v_cvt_pk_bf16_f32 v178, v186, v187
	v_cvt_pk_bf16_f32 v179, v182, v183
	v_cvt_pk_bf16_f32 v180, v188, v189
	v_cvt_pk_bf16_f32 v181, v184, v185
	global_store_dwordx4 v[210:211], v[178:181], off offset:256
	v_mov_b32_e32 v188, 0
	v_mov_b32_e32 v189, 0
	v_lshlrev_b32_e32 v180, 16, v174
	v_and_b32_e32 v181, 0xffff0000, v174
	v_mul_f32_e32 v174, 0xbfb8aa3b, v118
	v_exp_f32_e32 v182, v174
	v_mul_f32_e32 v174, 0xbfb8aa3b, v119
	v_exp_f32_e32 v183, v174
	v_lshl_add_u64 v[178:179], v[210:211], 0, s[56:57]
	v_pk_add_f32 v[182:183], v[182:183], 1.0 op_sel_hi:[1,0]
	s_nop 0
	s_nop 0
	v_rcp_f32_e32 v183, v183
	s_nop 0
	s_nop 0
	v_rcp_f32_e32 v182, v182
	s_nop 0
	v_lshlrev_b32_e32 v184, 16, v170
	v_and_b32_e32 v185, 0xffff0000, v170
	v_mul_f32_e32 v170, 0xbfb8aa3b, v120
	v_pk_fma_f32 v[180:181], v[182:183], v[180:181], v[184:185]
	v_exp_f32_e32 v182, v170
	v_mul_f32_e32 v170, 0xbfb8aa3b, v121
	v_exp_f32_e32 v183, v170
	v_lshlrev_b32_e32 v174, 16, v175
	v_and_b32_e32 v175, 0xffff0000, v175
	v_pk_add_f32 v[182:183], v[182:183], 1.0 op_sel_hi:[1,0]
	s_nop 0
	s_nop 0
	v_rcp_f32_e32 v183, v183
	s_nop 0
	s_nop 0
	v_rcp_f32_e32 v182, v182
	s_nop 0
	v_lshlrev_b32_e32 v170, 16, v171
	v_and_b32_e32 v171, 0xffff0000, v171
	v_pk_fma_f32 v[174:175], v[182:183], v[174:175], v[170:171]
	v_lshlrev_b32_e32 v170, 16, v176
	v_and_b32_e32 v171, 0xffff0000, v176
	v_mul_f32_e32 v176, 0xbfb8aa3b, v114
	v_exp_f32_e32 v182, v176
	v_mul_f32_e32 v176, 0xbfb8aa3b, v115
	v_exp_f32_e32 v183, v176
	s_nop 0
	v_pk_add_f32 v[182:183], v[182:183], 1.0 op_sel_hi:[1,0]
	s_nop 0
	s_nop 0
	v_rcp_f32_e32 v183, v183
	s_nop 0
	s_nop 0
	v_lshlrev_b32_e32 v184, 16, v172
	v_and_b32_e32 v185, 0xffff0000, v172
	v_mul_f32_e32 v172, 0xbfb8aa3b, v116
	v_rcp_f32_e32 v182, v182
	s_nop 0
	v_exp_f32_e32 v176, v172
	v_mul_f32_e32 v172, 0xbfb8aa3b, v117
	v_pk_fma_f32 v[182:183], v[182:183], v[170:171], v[184:185]
	v_lshlrev_b32_e32 v170, 16, v177
	v_and_b32_e32 v171, 0xffff0000, v177
	v_exp_f32_e32 v177, v172
	s_nop 0
	v_pk_add_f32 v[176:177], v[176:177], 1.0 op_sel_hi:[1,0]
	s_nop 0
	s_nop 0
	v_rcp_f32_e32 v177, v177
	s_nop 0
	s_nop 0
	v_rcp_f32_e32 v176, v176
	s_nop 0
	v_lshlrev_b32_e32 v172, 16, v173
	v_and_b32_e32 v173, 0xffff0000, v173
	v_pk_fma_f32 v[176:177], v[176:177], v[170:171], v[172:173]
	v_cvt_pk_bf16_f32 v170, v180, v181
	v_cvt_pk_bf16_f32 v171, v174, v175
	v_cvt_pk_bf16_f32 v172, v182, v183
	v_cvt_pk_bf16_f32 v173, v176, v177
	global_store_dwordx4 v[178:179], v[170:173], off
	v_mov_b32_e32 v186, 0
	v_mov_b32_e32 v187, 0
	v_lshlrev_b32_e32 v170, 16, v166
	v_and_b32_e32 v171, 0xffff0000, v166
	v_mul_f32_e32 v166, 0xbfb8aa3b, v94
	v_exp_f32_e32 v172, v166
	v_mul_f32_e32 v166, 0xbfb8aa3b, v95
	v_exp_f32_e32 v173, v166
	s_nop 0
	v_pk_add_f32 v[172:173], v[172:173], 1.0 op_sel_hi:[1,0]
	s_nop 0
	s_nop 0
	v_rcp_f32_e32 v173, v173
	s_nop 0
	s_nop 0
	v_rcp_f32_e32 v172, v172
	s_nop 0
	v_lshlrev_b32_e32 v174, 16, v162
	v_and_b32_e32 v175, 0xffff0000, v162
	v_mul_f32_e32 v162, 0xbfb8aa3b, v96
	v_pk_fma_f32 v[170:171], v[172:173], v[170:171], v[174:175]
	v_exp_f32_e32 v172, v162
	v_mul_f32_e32 v162, 0xbfb8aa3b, v97
	v_exp_f32_e32 v173, v162
	v_lshlrev_b32_e32 v166, 16, v167
	v_and_b32_e32 v167, 0xffff0000, v167
	v_pk_add_f32 v[172:173], v[172:173], 1.0 op_sel_hi:[1,0]
	s_nop 0
	s_nop 0
	v_rcp_f32_e32 v173, v173
	s_nop 0
	s_nop 0
	v_rcp_f32_e32 v172, v172
	s_nop 0
	v_lshlrev_b32_e32 v162, 16, v163
	v_and_b32_e32 v163, 0xffff0000, v163
	v_pk_fma_f32 v[166:167], v[172:173], v[166:167], v[162:163]
	v_lshlrev_b32_e32 v162, 16, v168
	v_and_b32_e32 v163, 0xffff0000, v168
	v_mul_f32_e32 v168, 0xbfb8aa3b, v90
	v_exp_f32_e32 v172, v168
	v_mul_f32_e32 v168, 0xbfb8aa3b, v91
	v_exp_f32_e32 v173, v168
	s_nop 0
	v_pk_add_f32 v[172:173], v[172:173], 1.0 op_sel_hi:[1,0]
	s_nop 0
	s_nop 0
	v_rcp_f32_e32 v173, v173
	s_nop 0
	s_nop 0
	v_lshlrev_b32_e32 v174, 16, v164
	v_and_b32_e32 v175, 0xffff0000, v164
	v_mul_f32_e32 v164, 0xbfb8aa3b, v92
	v_rcp_f32_e32 v172, v172
	s_nop 0
	v_exp_f32_e32 v168, v164
	v_mul_f32_e32 v164, 0xbfb8aa3b, v93
	v_pk_fma_f32 v[172:173], v[172:173], v[162:163], v[174:175]
	v_lshlrev_b32_e32 v162, 16, v169
	v_and_b32_e32 v163, 0xffff0000, v169
	v_exp_f32_e32 v169, v164
	s_nop 0
	v_pk_add_f32 v[168:169], v[168:169], 1.0 op_sel_hi:[1,0]
	s_nop 0
	s_nop 0
	v_rcp_f32_e32 v169, v169
	s_nop 0
	s_nop 0
	v_rcp_f32_e32 v168, v168
	s_nop 0
	v_lshlrev_b32_e32 v164, 16, v165
	v_and_b32_e32 v165, 0xffff0000, v165
	v_pk_fma_f32 v[168:169], v[168:169], v[162:163], v[164:165]
	v_cvt_pk_bf16_f32 v162, v170, v171
	v_cvt_pk_bf16_f32 v163, v166, v167
	v_cvt_pk_bf16_f32 v164, v172, v173
	v_cvt_pk_bf16_f32 v165, v168, v169
	global_store_dwordx4 v[178:179], v[162:165], off offset:256
	s_nop 1
	v_lshlrev_b32_e32 v164, 16, v158
	v_and_b32_e32 v165, 0xffff0000, v158
	v_mul_f32_e32 v158, 0xbfb8aa3b, v102
	v_exp_f32_e32 v166, v158
	v_mul_f32_e32 v158, 0xbfb8aa3b, v103
	v_exp_f32_e32 v167, v158
	v_lshl_add_u64 v[162:163], v[178:179], 0, s[56:57]
	v_lshl_add_u64 v[210:211], v[162:163], 0, s[56:57]
	v_mov_b32_e32 v178, 0
	v_pk_add_f32 v[166:167], v[166:167], 1.0 op_sel_hi:[1,0]
	s_nop 0
	s_nop 0
	v_rcp_f32_e32 v167, v167
	s_nop 0
	s_nop 0
	v_rcp_f32_e32 v166, v166
	s_nop 0
	v_lshlrev_b32_e32 v168, 16, v154
	v_and_b32_e32 v169, 0xffff0000, v154
	v_mul_f32_e32 v154, 0xbfb8aa3b, v104
	v_pk_fma_f32 v[164:165], v[166:167], v[164:165], v[168:169]
	v_exp_f32_e32 v166, v154
	v_mul_f32_e32 v154, 0xbfb8aa3b, v105
	v_exp_f32_e32 v167, v154
	v_lshlrev_b32_e32 v158, 16, v159
	v_and_b32_e32 v159, 0xffff0000, v159
	v_pk_add_f32 v[166:167], v[166:167], 1.0 op_sel_hi:[1,0]
	s_nop 0
	s_nop 0
	v_rcp_f32_e32 v167, v167
	s_nop 0
	s_nop 0
	v_rcp_f32_e32 v166, v166
	s_nop 0
	v_lshlrev_b32_e32 v154, 16, v155
	v_and_b32_e32 v155, 0xffff0000, v155
	v_pk_fma_f32 v[158:159], v[166:167], v[158:159], v[154:155]
	v_lshlrev_b32_e32 v154, 16, v160
	v_and_b32_e32 v155, 0xffff0000, v160
	v_mul_f32_e32 v160, 0xbfb8aa3b, v98
	v_exp_f32_e32 v166, v160
	v_mul_f32_e32 v160, 0xbfb8aa3b, v99
	v_exp_f32_e32 v167, v160
	s_nop 0
	v_pk_add_f32 v[166:167], v[166:167], 1.0 op_sel_hi:[1,0]
	s_nop 0
	s_nop 0
	v_rcp_f32_e32 v167, v167
	s_nop 0
	s_nop 0
	v_lshlrev_b32_e32 v168, 16, v156
	v_and_b32_e32 v169, 0xffff0000, v156
	v_mul_f32_e32 v156, 0xbfb8aa3b, v100
	v_rcp_f32_e32 v166, v166
	s_nop 0
	v_exp_f32_e32 v160, v156
	v_mul_f32_e32 v156, 0xbfb8aa3b, v101
	v_pk_fma_f32 v[166:167], v[166:167], v[154:155], v[168:169]
	v_lshlrev_b32_e32 v154, 16, v161
	v_and_b32_e32 v155, 0xffff0000, v161
	v_exp_f32_e32 v161, v156
	s_nop 0
	v_pk_add_f32 v[160:161], v[160:161], 1.0 op_sel_hi:[1,0]
	s_nop 0
	s_nop 0
	v_rcp_f32_e32 v161, v161
	s_nop 0
	s_nop 0
	v_rcp_f32_e32 v160, v160
	s_nop 0
	v_lshlrev_b32_e32 v156, 16, v157
	v_and_b32_e32 v157, 0xffff0000, v157
	v_pk_fma_f32 v[160:161], v[160:161], v[154:155], v[156:157]
	v_cvt_pk_bf16_f32 v154, v164, v165
	v_cvt_pk_bf16_f32 v155, v158, v159
	v_cvt_pk_bf16_f32 v156, v166, v167
	v_cvt_pk_bf16_f32 v157, v160, v161
	global_store_dwordx4 v[162:163], v[154:157], off
	s_nop 1
	v_lshlrev_b32_e32 v154, 16, v150
	v_and_b32_e32 v155, 0xffff0000, v150
	v_mul_f32_e32 v150, 0xbfb8aa3b, v78
	v_exp_f32_e32 v156, v150
	v_mul_f32_e32 v150, 0xbfb8aa3b, v79
	v_exp_f32_e32 v157, v150
	s_nop 0
	v_pk_add_f32 v[156:157], v[156:157], 1.0 op_sel_hi:[1,0]
	s_nop 0
	s_nop 0
	v_rcp_f32_e32 v157, v157
	s_nop 0
	s_nop 0
	v_rcp_f32_e32 v156, v156
	s_nop 0
	v_lshlrev_b32_e32 v158, 16, v146
	v_and_b32_e32 v159, 0xffff0000, v146
	v_mul_f32_e32 v146, 0xbfb8aa3b, v80
	v_pk_fma_f32 v[154:155], v[156:157], v[154:155], v[158:159]
	v_exp_f32_e32 v156, v146
	v_mul_f32_e32 v146, 0xbfb8aa3b, v81
	v_exp_f32_e32 v157, v146
	v_lshlrev_b32_e32 v150, 16, v151
	v_and_b32_e32 v151, 0xffff0000, v151
	v_pk_add_f32 v[156:157], v[156:157], 1.0 op_sel_hi:[1,0]
	s_nop 0
	s_nop 0
	v_rcp_f32_e32 v157, v157
	s_nop 0
	s_nop 0
	v_rcp_f32_e32 v156, v156
	s_nop 0
	v_lshlrev_b32_e32 v146, 16, v147
	v_and_b32_e32 v147, 0xffff0000, v147
	v_pk_fma_f32 v[150:151], v[156:157], v[150:151], v[146:147]
	v_lshlrev_b32_e32 v146, 16, v152
	v_and_b32_e32 v147, 0xffff0000, v152
	v_mul_f32_e32 v152, 0xbfb8aa3b, v74
	v_exp_f32_e32 v156, v152
	v_mul_f32_e32 v152, 0xbfb8aa3b, v75
	v_exp_f32_e32 v157, v152
	s_nop 0
	v_pk_add_f32 v[156:157], v[156:157], 1.0 op_sel_hi:[1,0]
	s_nop 0
	s_nop 0
	v_rcp_f32_e32 v157, v157
	s_nop 0
	s_nop 0
	v_lshlrev_b32_e32 v158, 16, v148
	v_and_b32_e32 v159, 0xffff0000, v148
	v_mul_f32_e32 v148, 0xbfb8aa3b, v76
	v_rcp_f32_e32 v156, v156
	s_nop 0
	v_exp_f32_e32 v152, v148
	v_mul_f32_e32 v148, 0xbfb8aa3b, v77
	v_pk_fma_f32 v[156:157], v[156:157], v[146:147], v[158:159]
	v_lshlrev_b32_e32 v146, 16, v153
	v_and_b32_e32 v147, 0xffff0000, v153
	v_exp_f32_e32 v153, v148
	s_nop 0
	v_pk_add_f32 v[152:153], v[152:153], 1.0 op_sel_hi:[1,0]
	s_nop 0
	s_nop 0
	v_rcp_f32_e32 v153, v153
	s_nop 0
	s_nop 0
	v_rcp_f32_e32 v152, v152
	s_nop 0
	v_lshlrev_b32_e32 v148, 16, v149
	v_and_b32_e32 v149, 0xffff0000, v149
	v_pk_fma_f32 v[152:153], v[152:153], v[146:147], v[148:149]
	v_cvt_pk_bf16_f32 v146, v154, v155
	v_cvt_pk_bf16_f32 v147, v150, v151
	v_cvt_pk_bf16_f32 v148, v156, v157
	v_cvt_pk_bf16_f32 v149, v152, v153
	global_store_dwordx4 v[162:163], v[146:149], off offset:256
	s_nop 1
	v_lshlrev_b32_e32 v146, 16, v142
	v_and_b32_e32 v147, 0xffff0000, v142
	v_mul_f32_e32 v142, 0xbfb8aa3b, v86
	v_exp_f32_e32 v148, v142
	v_mul_f32_e32 v142, 0xbfb8aa3b, v87
	v_exp_f32_e32 v149, v142
	s_nop 0
	v_pk_add_f32 v[148:149], v[148:149], 1.0 op_sel_hi:[1,0]
	s_nop 0
	s_nop 0
	v_rcp_f32_e32 v149, v149
	s_nop 0
	s_nop 0
	v_rcp_f32_e32 v148, v148
	s_nop 0
	v_lshlrev_b32_e32 v150, 16, v138
	v_and_b32_e32 v151, 0xffff0000, v138
	v_mul_f32_e32 v138, 0xbfb8aa3b, v88
	v_pk_fma_f32 v[146:147], v[148:149], v[146:147], v[150:151]
	v_exp_f32_e32 v148, v138
	v_mul_f32_e32 v138, 0xbfb8aa3b, v89
	v_exp_f32_e32 v149, v138
	v_lshlrev_b32_e32 v142, 16, v143
	v_and_b32_e32 v143, 0xffff0000, v143
	v_pk_add_f32 v[148:149], v[148:149], 1.0 op_sel_hi:[1,0]
	s_nop 0
	s_nop 0
	v_rcp_f32_e32 v149, v149
	s_nop 0
	s_nop 0
	v_rcp_f32_e32 v148, v148
	s_nop 0
	v_lshlrev_b32_e32 v138, 16, v139
	v_and_b32_e32 v139, 0xffff0000, v139
	v_pk_fma_f32 v[142:143], v[148:149], v[142:143], v[138:139]
	v_lshlrev_b32_e32 v138, 16, v144
	v_and_b32_e32 v139, 0xffff0000, v144
	v_mul_f32_e32 v144, 0xbfb8aa3b, v82
	v_exp_f32_e32 v148, v144
	v_mul_f32_e32 v144, 0xbfb8aa3b, v83
	v_exp_f32_e32 v149, v144
	s_nop 0
	v_pk_add_f32 v[148:149], v[148:149], 1.0 op_sel_hi:[1,0]
	s_nop 0
	s_nop 0
	v_rcp_f32_e32 v149, v149
	s_nop 0
	s_nop 0
	v_lshlrev_b32_e32 v150, 16, v140
	v_and_b32_e32 v151, 0xffff0000, v140
	v_mul_f32_e32 v140, 0xbfb8aa3b, v84
	v_rcp_f32_e32 v148, v148
	s_nop 0
	v_exp_f32_e32 v144, v140
	v_mul_f32_e32 v140, 0xbfb8aa3b, v85
	v_pk_fma_f32 v[148:149], v[148:149], v[138:139], v[150:151]
	v_lshlrev_b32_e32 v138, 16, v145
	v_and_b32_e32 v139, 0xffff0000, v145
	v_exp_f32_e32 v145, v140
	s_nop 0
	v_pk_add_f32 v[144:145], v[144:145], 1.0 op_sel_hi:[1,0]
	s_nop 0
	s_nop 0
	v_rcp_f32_e32 v145, v145
	s_nop 0
	s_nop 0
	v_rcp_f32_e32 v144, v144
	s_nop 0
	v_lshlrev_b32_e32 v140, 16, v141
	v_and_b32_e32 v141, 0xffff0000, v141
	v_pk_fma_f32 v[144:145], v[144:145], v[138:139], v[140:141]
	v_cvt_pk_bf16_f32 v138, v146, v147
	v_cvt_pk_bf16_f32 v139, v142, v143
	v_cvt_pk_bf16_f32 v140, v148, v149
	v_cvt_pk_bf16_f32 v141, v144, v145
	global_store_dwordx4 v[210:211], v[138:141], off
	s_nop 1
	v_lshlrev_b32_e32 v138, 16, v134
	v_and_b32_e32 v139, 0xffff0000, v134
	v_mul_f32_e32 v134, 0xbfb8aa3b, v70
	v_exp_f32_e32 v140, v134
	v_mul_f32_e32 v134, 0xbfb8aa3b, v71
	v_exp_f32_e32 v141, v134
	s_nop 0
	v_pk_add_f32 v[140:141], v[140:141], 1.0 op_sel_hi:[1,0]
	s_nop 0
	s_nop 0
	v_rcp_f32_e32 v141, v141
	s_nop 0
	s_nop 0
	v_rcp_f32_e32 v140, v140
	s_nop 0
	v_lshlrev_b32_e32 v142, 16, v130
	v_and_b32_e32 v143, 0xffff0000, v130
	v_mul_f32_e32 v130, 0xbfb8aa3b, v72
	v_pk_fma_f32 v[138:139], v[140:141], v[138:139], v[142:143]
	v_exp_f32_e32 v140, v130
	v_mul_f32_e32 v130, 0xbfb8aa3b, v73
	v_exp_f32_e32 v141, v130
	v_lshlrev_b32_e32 v134, 16, v135
	v_and_b32_e32 v135, 0xffff0000, v135
	v_pk_add_f32 v[140:141], v[140:141], 1.0 op_sel_hi:[1,0]
	s_nop 0
	s_nop 0
	v_rcp_f32_e32 v141, v141
	s_nop 0
	s_nop 0
	v_rcp_f32_e32 v140, v140
	s_nop 0
	v_lshlrev_b32_e32 v130, 16, v131
	v_and_b32_e32 v131, 0xffff0000, v131
	v_pk_fma_f32 v[134:135], v[140:141], v[134:135], v[130:131]
	v_lshlrev_b32_e32 v130, 16, v136
	v_and_b32_e32 v131, 0xffff0000, v136
	v_mul_f32_e32 v136, 0xbfb8aa3b, v66
	v_exp_f32_e32 v140, v136
	v_mul_f32_e32 v136, 0xbfb8aa3b, v67
	v_exp_f32_e32 v141, v136
	s_nop 0
	v_pk_add_f32 v[140:141], v[140:141], 1.0 op_sel_hi:[1,0]
	s_nop 0
	s_nop 0
	v_rcp_f32_e32 v141, v141
	s_nop 0
	s_nop 0
	v_lshlrev_b32_e32 v142, 16, v132
	v_and_b32_e32 v143, 0xffff0000, v132
	v_mul_f32_e32 v132, 0xbfb8aa3b, v68
	v_rcp_f32_e32 v140, v140
	s_nop 0
	v_exp_f32_e32 v136, v132
	v_mul_f32_e32 v132, 0xbfb8aa3b, v69
	v_pk_fma_f32 v[140:141], v[140:141], v[130:131], v[142:143]
	v_lshlrev_b32_e32 v130, 16, v137
	v_and_b32_e32 v131, 0xffff0000, v137
	v_exp_f32_e32 v137, v132
	s_nop 0
	v_pk_add_f32 v[136:137], v[136:137], 1.0 op_sel_hi:[1,0]
	s_nop 0
	s_nop 0
	v_rcp_f32_e32 v137, v137
	s_nop 0
	s_nop 0
	v_rcp_f32_e32 v136, v136
	s_nop 0
	v_lshlrev_b32_e32 v132, 16, v133
	v_and_b32_e32 v133, 0xffff0000, v133
	v_pk_fma_f32 v[136:137], v[136:137], v[130:131], v[132:133]
	v_cvt_pk_bf16_f32 v130, v138, v139
	v_cvt_pk_bf16_f32 v131, v134, v135
	v_cvt_pk_bf16_f32 v132, v140, v141
	v_cvt_pk_bf16_f32 v133, v136, v137
	global_store_dwordx4 v[210:211], v[130:133], off offset:256
	s_nop 1
	v_add_co_u32_e32 v130, vcc, 0x10000, v208
	s_nop 1
	v_addc_co_u32_e32 v131, vcc, 0, v209, vcc
	s_and_b64 vcc, exec, s[0:1]
	s_cbranch_vccnz .LBB0_1078
	v_add_co_u32_e32 v130, vcc, 0x30000, v208
	s_nop 1
	v_addc_co_u32_e32 v131, vcc, 0, v209, vcc
	global_load_dwordx4 v[186:189], v[130:131], off
.LBB0_1078:
	v_add_co_u32_e32 v130, vcc, 0x10000, v208
	v_mov_b32_e32 v179, 0
	s_nop 0
	v_addc_co_u32_e32 v131, vcc, 0, v209, vcc
	s_and_b64 vcc, exec, s[0:1]
	v_mov_b32_e32 v180, 0
	v_mov_b32_e32 v181, 0
	s_cbranch_vccnz .LBB0_1080
	v_add_co_u32_e32 v130, vcc, 0x30000, v208
	s_nop 1
	v_addc_co_u32_e32 v131, vcc, 0, v209, vcc
	global_load_dwordx4 v[178:181], v[130:131], off offset:256
.LBB0_1080:
	v_add_co_u32_e32 v130, vcc, 0x12000, v208
	v_mov_b32_e32 v162, 0
	s_nop 0
	v_addc_co_u32_e32 v131, vcc, 0, v209, vcc
	s_and_b64 vcc, exec, s[0:1]
	v_mov_b32_e32 v170, 0
	v_mov_b32_e32 v171, 0
	v_mov_b32_e32 v172, 0
	v_mov_b32_e32 v173, 0
	s_cbranch_vccnz .LBB0_1082
	v_add_co_u32_e32 v130, vcc, 0x32000, v208
	s_nop 1
	v_addc_co_u32_e32 v131, vcc, 0, v209, vcc
	global_load_dwordx4 v[170:173], v[130:131], off
.LBB0_1082:
	v_add_co_u32_e32 v130, vcc, 0x12000, v208
	v_mov_b32_e32 v163, 0
	s_nop 0
	v_addc_co_u32_e32 v131, vcc, 0, v209, vcc
	s_and_b64 vcc, exec, s[0:1]
	v_mov_b32_e32 v164, 0
	v_mov_b32_e32 v165, 0
	s_cbranch_vccnz .LBB0_1084
	v_add_co_u32_e32 v130, vcc, 0x32000, v208
	s_nop 1
	v_addc_co_u32_e32 v131, vcc, 0, v209, vcc
	global_load_dwordx4 v[162:165], v[130:131], off offset:256
.LBB0_1084:
	v_add_co_u32_e32 v130, vcc, 0x14000, v208
	v_mov_b32_e32 v146, 0
	s_nop 0
	v_addc_co_u32_e32 v131, vcc, 0, v209, vcc
	s_and_b64 vcc, exec, s[0:1]
	v_mov_b32_e32 v154, 0
	v_mov_b32_e32 v155, 0
	v_mov_b32_e32 v156, 0
	v_mov_b32_e32 v157, 0
	s_cbranch_vccnz .LBB0_1086
	v_add_co_u32_e32 v130, vcc, 0x34000, v208
	s_nop 1
	v_addc_co_u32_e32 v131, vcc, 0, v209, vcc
	global_load_dwordx4 v[154:157], v[130:131], off
.LBB0_1086:
	v_add_co_u32_e32 v130, vcc, 0x14000, v208
	v_mov_b32_e32 v147, 0
	s_nop 0
	v_addc_co_u32_e32 v131, vcc, 0, v209, vcc
	s_and_b64 vcc, exec, s[0:1]
	v_mov_b32_e32 v148, 0
	v_mov_b32_e32 v149, 0
	s_cbranch_vccnz .LBB0_1088
	v_add_co_u32_e32 v130, vcc, 0x34000, v208
	s_nop 1
	v_addc_co_u32_e32 v131, vcc, 0, v209, vcc
	global_load_dwordx4 v[146:149], v[130:131], off offset:256

.LBB0_1092:
	s_waitcnt vmcnt(0)
	v_mov_b32_e32 v190, v194
	v_mov_b32_e32 v191, v195
	v_mov_b32_e32 v192, v196
	v_mov_b32_e32 v193, v197
	v_mov_b32_e32 v182, v226
	v_mov_b32_e32 v183, v227
	v_mov_b32_e32 v184, v228
	v_mov_b32_e32 v185, v229
	v_mov_b32_e32 v174, v230
	v_mov_b32_e32 v175, v231
	v_mov_b32_e32 v176, v232
	v_mov_b32_e32 v177, v233
	v_mov_b32_e32 v166, v234
	v_mov_b32_e32 v167, v235
	v_mov_b32_e32 v168, v236
	v_mov_b32_e32 v169, v237
	v_mov_b32_e32 v158, v242
	v_mov_b32_e32 v159, v243
	v_mov_b32_e32 v160, v244
	v_mov_b32_e32 v161, v245
	v_mov_b32_e32 v150, v246
	v_mov_b32_e32 v151, v247
	v_mov_b32_e32 v152, v248
	v_mov_b32_e32 v153, v249
	v_lshlrev_b32_e32 v212, 16, v190
	v_and_b32_e32 v213, 0xffff0000, v190
	v_mul_f32_e32 v190, 0xbfb8aa3b, v62
	v_exp_f32_e32 v218, v190
	v_mul_f32_e32 v190, 0xbfb8aa3b, v63
	v_exp_f32_e32 v219, v190
	s_mul_i32 s0, s24, 0xa0
	s_mov_b32 s1, s57
	v_lshl_add_u64 v[210:211], v[210:211], 0, s[0:1]
	v_pk_add_f32 v[218:219], v[218:219], 1.0 op_sel_hi:[1,0]
	s_mov_b64 s[24:25], 0
	s_nop 0
	v_rcp_f32_e32 v219, v219
	s_nop 0
	s_nop 0
	v_rcp_f32_e32 v218, v218
	s_nop 0
	v_lshlrev_b32_e32 v220, 16, v186
	v_and_b32_e32 v221, 0xffff0000, v186
	v_mul_f32_e32 v186, 0xbfb8aa3b, v64
	v_pk_fma_f32 v[212:213], v[218:219], v[212:213], v[220:221]
	v_exp_f32_e32 v218, v186
	v_mul_f32_e32 v186, 0xbfb8aa3b, v65
	v_exp_f32_e32 v219, v186
	v_lshlrev_b32_e32 v190, 16, v191
	v_and_b32_e32 v191, 0xffff0000, v191
	v_pk_add_f32 v[218:219], v[218:219], 1.0 op_sel_hi:[1,0]
	s_nop 0
	s_nop 0
	v_rcp_f32_e32 v219, v219
	s_nop 0
	s_nop 0
	v_rcp_f32_e32 v218, v218
	s_nop 0
	v_lshlrev_b32_e32 v186, 16, v187
	v_and_b32_e32 v187, 0xffff0000, v187
	v_pk_fma_f32 v[190:191], v[218:219], v[190:191], v[186:187]
	v_lshlrev_b32_e32 v186, 16, v192
	v_and_b32_e32 v187, 0xffff0000, v192
	v_mul_f32_e32 v192, 0xbfb8aa3b, v58
	v_exp_f32_e32 v218, v192
	v_mul_f32_e32 v192, 0xbfb8aa3b, v59
	v_exp_f32_e32 v219, v192
	s_nop 0
	v_pk_add_f32 v[218:219], v[218:219], 1.0 op_sel_hi:[1,0]
	s_nop 0
	s_nop 0
	v_rcp_f32_e32 v219, v219
	s_nop 0
	s_nop 0
	v_lshlrev_b32_e32 v220, 16, v188
	v_and_b32_e32 v221, 0xffff0000, v188
	v_mul_f32_e32 v188, 0xbfb8aa3b, v60
	v_rcp_f32_e32 v218, v218
	s_nop 0
	v_exp_f32_e32 v192, v188
	v_mul_f32_e32 v188, 0xbfb8aa3b, v61
	v_pk_fma_f32 v[218:219], v[218:219], v[186:187], v[220:221]
	v_lshlrev_b32_e32 v186, 16, v193
	v_and_b32_e32 v187, 0xffff0000, v193
	v_exp_f32_e32 v193, v188
	s_nop 0
	v_pk_add_f32 v[192:193], v[192:193], 1.0 op_sel_hi:[1,0]
	s_nop 0
	s_nop 0
	v_rcp_f32_e32 v193, v193
	s_nop 0
	s_nop 0
	v_rcp_f32_e32 v192, v192
	s_nop 0
	v_lshlrev_b32_e32 v188, 16, v189
	v_and_b32_e32 v189, 0xffff0000, v189
	v_pk_fma_f32 v[192:193], v[192:193], v[186:187], v[188:189]
	v_cvt_pk_bf16_f32 v186, v212, v213
	v_cvt_pk_bf16_f32 v187, v190, v191
	v_cvt_pk_bf16_f32 v188, v218, v219
	v_cvt_pk_bf16_f32 v189, v192, v193
	global_store_dwordx4 v[210:211], v[186:189], off
	s_nop 1
	v_lshlrev_b32_e32 v186, 16, v182
	v_and_b32_e32 v187, 0xffff0000, v182
	v_mul_f32_e32 v182, 0xbfb8aa3b, v44
	v_exp_f32_e32 v188, v182
	v_mul_f32_e32 v182, 0xbfb8aa3b, v45
	v_exp_f32_e32 v189, v182
	s_nop 0
	v_pk_add_f32 v[188:189], v[188:189], 1.0 op_sel_hi:[1,0]
	s_nop 0
	s_nop 0
	v_rcp_f32_e32 v189, v189
	s_nop 0
	s_nop 0
	v_rcp_f32_e32 v188, v188
	s_nop 0
	v_lshlrev_b32_e32 v190, 16, v178
	v_and_b32_e32 v191, 0xffff0000, v178
	v_mul_f32_e32 v178, 0xbfb8aa3b, v46
	v_pk_fma_f32 v[186:187], v[188:189], v[186:187], v[190:191]
	v_exp_f32_e32 v188, v178
	v_mul_f32_e32 v178, 0xbfb8aa3b, v47
	v_exp_f32_e32 v189, v178
	v_lshlrev_b32_e32 v182, 16, v183
	v_and_b32_e32 v183, 0xffff0000, v183
	v_pk_add_f32 v[188:189], v[188:189], 1.0 op_sel_hi:[1,0]
	s_nop 0
	s_nop 0
	v_rcp_f32_e32 v189, v189
	s_nop 0
	s_nop 0
	v_rcp_f32_e32 v188, v188
	s_nop 0
	v_lshlrev_b32_e32 v178, 16, v179
	v_and_b32_e32 v179, 0xffff0000, v179
	v_pk_fma_f32 v[182:183], v[188:189], v[182:183], v[178:179]
	v_lshlrev_b32_e32 v178, 16, v184
	v_and_b32_e32 v179, 0xffff0000, v184
	v_mul_f32_e32 v184, 0xbfb8aa3b, v40
	v_exp_f32_e32 v188, v184
	v_mul_f32_e32 v184, 0xbfb8aa3b, v41
	v_exp_f32_e32 v189, v184
	s_nop 0
	v_pk_add_f32 v[188:189], v[188:189], 1.0 op_sel_hi:[1,0]
	s_nop 0
	s_nop 0
	v_rcp_f32_e32 v189, v189
	s_nop 0
	s_nop 0
	v_lshlrev_b32_e32 v190, 16, v180
	v_and_b32_e32 v191, 0xffff0000, v180
	v_mul_f32_e32 v180, 0xbfb8aa3b, v42
	v_rcp_f32_e32 v188, v188
	s_nop 0
	v_exp_f32_e32 v184, v180
	v_mul_f32_e32 v180, 0xbfb8aa3b, v43
	v_pk_fma_f32 v[188:189], v[188:189], v[178:179], v[190:191]
	v_lshlrev_b32_e32 v178, 16, v185
	v_and_b32_e32 v179, 0xffff0000, v185
	v_exp_f32_e32 v185, v180
	s_nop 0
	v_pk_add_f32 v[184:185], v[184:185], 1.0 op_sel_hi:[1,0]
	s_nop 0
	s_nop 0
	v_rcp_f32_e32 v185, v185
	s_nop 0
	s_nop 0
	v_rcp_f32_e32 v184, v184
	s_nop 0
	v_lshlrev_b32_e32 v180, 16, v181
	v_and_b32_e32 v181, 0xffff0000, v181
	v_pk_fma_f32 v[184:185], v[184:185], v[178:179], v[180:181]
	v_cvt_pk_bf16_f32 v178, v186, v187
	v_cvt_pk_bf16_f32 v179, v182, v183
	v_cvt_pk_bf16_f32 v180, v188, v189
	v_cvt_pk_bf16_f32 v181, v184, v185
	global_store_dwordx4 v[210:211], v[178:181], off offset:256
	s_nop 1
	v_lshlrev_b32_e32 v180, 16, v174
	v_and_b32_e32 v181, 0xffff0000, v174
	v_mul_f32_e32 v174, 0xbfb8aa3b, v54
	v_exp_f32_e32 v182, v174
	v_mul_f32_e32 v174, 0xbfb8aa3b, v55
	v_exp_f32_e32 v183, v174
	v_lshl_add_u64 v[178:179], v[210:211], 0, s[56:57]
	v_pk_add_f32 v[182:183], v[182:183], 1.0 op_sel_hi:[1,0]
	s_nop 0
	s_nop 0
	v_rcp_f32_e32 v183, v183
	s_nop 0
	s_nop 0
	v_rcp_f32_e32 v182, v182
	s_nop 0
	v_lshlrev_b32_e32 v184, 16, v170
	v_and_b32_e32 v185, 0xffff0000, v170
	v_mul_f32_e32 v170, 0xbfb8aa3b, v56
	v_pk_fma_f32 v[180:181], v[182:183], v[180:181], v[184:185]
	v_exp_f32_e32 v182, v170
	v_mul_f32_e32 v170, 0xbfb8aa3b, v57
	v_exp_f32_e32 v183, v170
	v_lshlrev_b32_e32 v174, 16, v175
	v_and_b32_e32 v175, 0xffff0000, v175
	v_pk_add_f32 v[182:183], v[182:183], 1.0 op_sel_hi:[1,0]
	s_nop 0
	s_nop 0
	v_rcp_f32_e32 v183, v183
	s_nop 0
	s_nop 0
	v_rcp_f32_e32 v182, v182
	s_nop 0
	v_lshlrev_b32_e32 v170, 16, v171
	v_and_b32_e32 v171, 0xffff0000, v171
	v_pk_fma_f32 v[174:175], v[182:183], v[174:175], v[170:171]
	v_lshlrev_b32_e32 v170, 16, v176
	v_and_b32_e32 v171, 0xffff0000, v176
	v_mul_f32_e32 v176, 0xbfb8aa3b, v50
	v_exp_f32_e32 v182, v176
	v_mul_f32_e32 v176, 0xbfb8aa3b, v51
	v_exp_f32_e32 v183, v176
	s_nop 0
	v_pk_add_f32 v[182:183], v[182:183], 1.0 op_sel_hi:[1,0]
	s_nop 0
	s_nop 0
	v_rcp_f32_e32 v183, v183
	s_nop 0
	s_nop 0
	v_lshlrev_b32_e32 v184, 16, v172
	v_and_b32_e32 v185, 0xffff0000, v172
	v_mul_f32_e32 v172, 0xbfb8aa3b, v52
	v_rcp_f32_e32 v182, v182
	s_nop 0
	v_exp_f32_e32 v176, v172
	v_mul_f32_e32 v172, 0xbfb8aa3b, v53
	v_pk_fma_f32 v[182:183], v[182:183], v[170:171], v[184:185]
	v_lshlrev_b32_e32 v170, 16, v177
	v_and_b32_e32 v171, 0xffff0000, v177
	v_exp_f32_e32 v177, v172
	s_nop 0
	v_pk_add_f32 v[176:177], v[176:177], 1.0 op_sel_hi:[1,0]
	s_nop 0
	s_nop 0
	v_rcp_f32_e32 v177, v177
	s_nop 0
	s_nop 0
	v_rcp_f32_e32 v176, v176
	s_nop 0
	v_lshlrev_b32_e32 v172, 16, v173
	v_and_b32_e32 v173, 0xffff0000, v173
	v_pk_fma_f32 v[176:177], v[176:177], v[170:171], v[172:173]
	v_cvt_pk_bf16_f32 v170, v180, v181
	v_cvt_pk_bf16_f32 v171, v174, v175
	v_cvt_pk_bf16_f32 v172, v182, v183
	v_cvt_pk_bf16_f32 v173, v176, v177
	global_store_dwordx4 v[178:179], v[170:173], off
	s_nop 1
	v_lshlrev_b32_e32 v170, 16, v166
	v_and_b32_e32 v171, 0xffff0000, v166
	v_mul_f32_e32 v166, 0xbfb8aa3b, v28
	v_exp_f32_e32 v172, v166
	v_mul_f32_e32 v166, 0xbfb8aa3b, v29
	v_exp_f32_e32 v173, v166
	s_nop 0
	v_pk_add_f32 v[172:173], v[172:173], 1.0 op_sel_hi:[1,0]
	s_nop 0
	s_nop 0
	v_rcp_f32_e32 v173, v173
	s_nop 0
	s_nop 0
	v_rcp_f32_e32 v172, v172
	s_nop 0
	v_lshlrev_b32_e32 v174, 16, v162
	v_and_b32_e32 v175, 0xffff0000, v162
	v_mul_f32_e32 v162, 0xbfb8aa3b, v30
	v_pk_fma_f32 v[170:171], v[172:173], v[170:171], v[174:175]
	v_exp_f32_e32 v172, v162
	v_mul_f32_e32 v162, 0xbfb8aa3b, v31
	v_exp_f32_e32 v173, v162
	v_lshlrev_b32_e32 v166, 16, v167
	v_and_b32_e32 v167, 0xffff0000, v167
	v_pk_add_f32 v[172:173], v[172:173], 1.0 op_sel_hi:[1,0]
	s_nop 0
	s_nop 0
	v_rcp_f32_e32 v173, v173
	s_nop 0
	s_nop 0
	v_rcp_f32_e32 v172, v172
	s_nop 0
	v_lshlrev_b32_e32 v162, 16, v163
	v_and_b32_e32 v163, 0xffff0000, v163
	v_pk_fma_f32 v[166:167], v[172:173], v[166:167], v[162:163]
	v_lshlrev_b32_e32 v162, 16, v168
	v_and_b32_e32 v163, 0xffff0000, v168
	v_mul_f32_e32 v168, 0xbfb8aa3b, v24
	v_exp_f32_e32 v172, v168
	v_mul_f32_e32 v168, 0xbfb8aa3b, v25
	v_exp_f32_e32 v173, v168
	s_nop 0
	v_pk_add_f32 v[172:173], v[172:173], 1.0 op_sel_hi:[1,0]
	s_nop 0
	s_nop 0
	v_rcp_f32_e32 v173, v173
	s_nop 0
	s_nop 0
	v_lshlrev_b32_e32 v174, 16, v164
	v_and_b32_e32 v175, 0xffff0000, v164
	v_mul_f32_e32 v164, 0xbfb8aa3b, v26
	v_rcp_f32_e32 v172, v172
	s_nop 0
	v_exp_f32_e32 v168, v164
	v_mul_f32_e32 v164, 0xbfb8aa3b, v27
	v_pk_fma_f32 v[172:173], v[172:173], v[162:163], v[174:175]
	v_lshlrev_b32_e32 v162, 16, v169
	v_and_b32_e32 v163, 0xffff0000, v169
	v_exp_f32_e32 v169, v164
	s_nop 0
	v_pk_add_f32 v[168:169], v[168:169], 1.0 op_sel_hi:[1,0]
	s_nop 0
	s_nop 0
	v_rcp_f32_e32 v169, v169
	s_nop 0
	s_nop 0
	v_rcp_f32_e32 v168, v168
	s_nop 0
	v_lshlrev_b32_e32 v164, 16, v165
	v_and_b32_e32 v165, 0xffff0000, v165
	v_pk_fma_f32 v[168:169], v[168:169], v[162:163], v[164:165]
	v_cvt_pk_bf16_f32 v162, v170, v171
	v_cvt_pk_bf16_f32 v163, v166, v167
	v_cvt_pk_bf16_f32 v164, v172, v173
	v_cvt_pk_bf16_f32 v165, v168, v169
	global_store_dwordx4 v[178:179], v[162:165], off offset:256
	s_nop 1
	v_lshlrev_b32_e32 v164, 16, v158
	v_and_b32_e32 v165, 0xffff0000, v158
	v_mul_f32_e32 v158, 0xbfb8aa3b, v36
	v_exp_f32_e32 v166, v158
	v_mul_f32_e32 v158, 0xbfb8aa3b, v37
	v_exp_f32_e32 v167, v158
	v_lshl_add_u64 v[162:163], v[178:179], 0, s[56:57]
	v_pk_add_f32 v[166:167], v[166:167], 1.0 op_sel_hi:[1,0]
	s_nop 0
	s_nop 0
	v_rcp_f32_e32 v167, v167
	s_nop 0
	s_nop 0
	v_rcp_f32_e32 v166, v166
	s_nop 0
	v_lshlrev_b32_e32 v168, 16, v154
	v_and_b32_e32 v169, 0xffff0000, v154
	v_mul_f32_e32 v154, 0xbfb8aa3b, v38
	v_pk_fma_f32 v[164:165], v[166:167], v[164:165], v[168:169]
	v_exp_f32_e32 v166, v154
	v_mul_f32_e32 v154, 0xbfb8aa3b, v39
	v_exp_f32_e32 v167, v154
	v_lshlrev_b32_e32 v158, 16, v159
	v_and_b32_e32 v159, 0xffff0000, v159
	v_pk_add_f32 v[166:167], v[166:167], 1.0 op_sel_hi:[1,0]
	s_nop 0
	s_nop 0
	v_rcp_f32_e32 v167, v167
	s_nop 0
	s_nop 0
	v_rcp_f32_e32 v166, v166
	s_nop 0
	v_lshlrev_b32_e32 v154, 16, v155
	v_and_b32_e32 v155, 0xffff0000, v155
	v_pk_fma_f32 v[158:159], v[166:167], v[158:159], v[154:155]
	v_lshlrev_b32_e32 v154, 16, v160
	v_and_b32_e32 v155, 0xffff0000, v160
	v_mul_f32_e32 v160, 0xbfb8aa3b, v32
	v_exp_f32_e32 v166, v160
	v_mul_f32_e32 v160, 0xbfb8aa3b, v33
	v_exp_f32_e32 v167, v160
	s_nop 0
	v_pk_add_f32 v[166:167], v[166:167], 1.0 op_sel_hi:[1,0]
	s_nop 0
	s_nop 0
	v_rcp_f32_e32 v167, v167
	s_nop 0
	s_nop 0
	v_lshlrev_b32_e32 v168, 16, v156
	v_and_b32_e32 v169, 0xffff0000, v156
	v_mul_f32_e32 v156, 0xbfb8aa3b, v34
	v_rcp_f32_e32 v166, v166
	s_nop 0
	v_exp_f32_e32 v160, v156
	v_mul_f32_e32 v156, 0xbfb8aa3b, v35
	v_pk_fma_f32 v[166:167], v[166:167], v[154:155], v[168:169]
	v_lshlrev_b32_e32 v154, 16, v161
	v_and_b32_e32 v155, 0xffff0000, v161
	v_exp_f32_e32 v161, v156
	s_nop 0
	v_pk_add_f32 v[160:161], v[160:161], 1.0 op_sel_hi:[1,0]
	s_nop 0
	s_nop 0
	v_rcp_f32_e32 v161, v161
	s_nop 0
	s_nop 0
	v_rcp_f32_e32 v160, v160
	s_nop 0
	v_lshlrev_b32_e32 v156, 16, v157
	v_and_b32_e32 v157, 0xffff0000, v157
	v_pk_fma_f32 v[160:161], v[160:161], v[154:155], v[156:157]
	v_cvt_pk_bf16_f32 v154, v164, v165
	v_cvt_pk_bf16_f32 v155, v158, v159
	v_cvt_pk_bf16_f32 v156, v166, v167
	v_cvt_pk_bf16_f32 v157, v160, v161
	global_store_dwordx4 v[162:163], v[154:157], off
	s_nop 1
	v_lshlrev_b32_e32 v154, 16, v150
	v_and_b32_e32 v155, 0xffff0000, v150
	v_mul_f32_e32 v150, 0xbfb8aa3b, v12
	v_exp_f32_e32 v156, v150
	v_mul_f32_e32 v150, 0xbfb8aa3b, v13
	v_exp_f32_e32 v157, v150
	s_nop 0
	v_pk_add_f32 v[156:157], v[156:157], 1.0 op_sel_hi:[1,0]
	s_nop 0
	s_nop 0
	v_rcp_f32_e32 v157, v157
	s_nop 0
	s_nop 0
	v_rcp_f32_e32 v156, v156
	s_nop 0
	v_lshlrev_b32_e32 v158, 16, v146
	v_and_b32_e32 v159, 0xffff0000, v146
	v_mul_f32_e32 v146, 0xbfb8aa3b, v14
	v_pk_fma_f32 v[154:155], v[156:157], v[154:155], v[158:159]
	v_exp_f32_e32 v156, v146
	v_mul_f32_e32 v146, 0xbfb8aa3b, v15
	v_exp_f32_e32 v157, v146
	v_lshlrev_b32_e32 v150, 16, v151
	v_and_b32_e32 v151, 0xffff0000, v151
	v_pk_add_f32 v[156:157], v[156:157], 1.0 op_sel_hi:[1,0]
	s_nop 0
	s_nop 0
	v_rcp_f32_e32 v157, v157
	s_nop 0
	s_nop 0
	v_rcp_f32_e32 v156, v156
	s_nop 0
	v_lshlrev_b32_e32 v146, 16, v147
	v_and_b32_e32 v147, 0xffff0000, v147
	v_pk_fma_f32 v[150:151], v[156:157], v[150:151], v[146:147]
	v_lshlrev_b32_e32 v146, 16, v152
	v_and_b32_e32 v147, 0xffff0000, v152
	v_mul_f32_e32 v152, 0xbfb8aa3b, v8
	v_exp_f32_e32 v156, v152
	v_mul_f32_e32 v152, 0xbfb8aa3b, v9
	v_exp_f32_e32 v157, v152
	s_nop 0
	v_pk_add_f32 v[156:157], v[156:157], 1.0 op_sel_hi:[1,0]
	s_nop 0
	s_nop 0
	v_rcp_f32_e32 v157, v157
	s_nop 0
	s_nop 0
	v_lshlrev_b32_e32 v158, 16, v148
	v_and_b32_e32 v159, 0xffff0000, v148
	v_mul_f32_e32 v148, 0xbfb8aa3b, v10
	v_rcp_f32_e32 v156, v156
	s_nop 0
	v_exp_f32_e32 v152, v148
	v_mul_f32_e32 v148, 0xbfb8aa3b, v11
	v_pk_fma_f32 v[156:157], v[156:157], v[146:147], v[158:159]
	v_lshlrev_b32_e32 v146, 16, v153
	v_and_b32_e32 v147, 0xffff0000, v153
	v_exp_f32_e32 v153, v148
	s_nop 0
	v_pk_add_f32 v[152:153], v[152:153], 1.0 op_sel_hi:[1,0]
	s_nop 0
	s_nop 0
	v_rcp_f32_e32 v153, v153
	s_nop 0
	s_nop 0
	v_rcp_f32_e32 v152, v152
	s_nop 0
	v_lshlrev_b32_e32 v148, 16, v149
	v_and_b32_e32 v149, 0xffff0000, v149
	v_pk_fma_f32 v[152:153], v[152:153], v[146:147], v[148:149]
	v_cvt_pk_bf16_f32 v146, v154, v155
	v_cvt_pk_bf16_f32 v147, v150, v151
	v_cvt_pk_bf16_f32 v148, v156, v157
	v_cvt_pk_bf16_f32 v149, v152, v153
	global_store_dwordx4 v[162:163], v[146:149], off offset:256
	s_nop 1
	v_lshlrev_b32_e32 v148, 16, v142
	v_and_b32_e32 v149, 0xffff0000, v142
	v_mul_f32_e32 v142, 0xbfb8aa3b, v20
	v_exp_f32_e32 v150, v142
	v_mul_f32_e32 v142, 0xbfb8aa3b, v21
	v_exp_f32_e32 v151, v142
	v_lshl_add_u64 v[146:147], v[162:163], 0, s[56:57]
	v_pk_add_f32 v[150:151], v[150:151], 1.0 op_sel_hi:[1,0]
	s_nop 0
	s_nop 0
	v_rcp_f32_e32 v151, v151
	s_nop 0
	s_nop 0
	v_rcp_f32_e32 v150, v150
	s_nop 0
	v_lshlrev_b32_e32 v152, 16, v138
	v_and_b32_e32 v153, 0xffff0000, v138
	v_mul_f32_e32 v138, 0xbfb8aa3b, v22
	v_pk_fma_f32 v[148:149], v[150:151], v[148:149], v[152:153]
	v_exp_f32_e32 v150, v138
	v_mul_f32_e32 v138, 0xbfb8aa3b, v23
	v_exp_f32_e32 v151, v138
	v_lshlrev_b32_e32 v142, 16, v143
	v_and_b32_e32 v143, 0xffff0000, v143
	v_pk_add_f32 v[150:151], v[150:151], 1.0 op_sel_hi:[1,0]
	s_nop 0
	s_nop 0
	v_rcp_f32_e32 v151, v151
	s_nop 0
	s_nop 0
	v_rcp_f32_e32 v150, v150
	s_nop 0
	v_lshlrev_b32_e32 v138, 16, v139
	v_and_b32_e32 v139, 0xffff0000, v139
	v_pk_fma_f32 v[142:143], v[150:151], v[142:143], v[138:139]
	v_lshlrev_b32_e32 v138, 16, v144
	v_and_b32_e32 v139, 0xffff0000, v144
	v_mul_f32_e32 v144, 0xbfb8aa3b, v16
	v_exp_f32_e32 v150, v144
	v_mul_f32_e32 v144, 0xbfb8aa3b, v17
	v_exp_f32_e32 v151, v144
	s_nop 0
	v_pk_add_f32 v[150:151], v[150:151], 1.0 op_sel_hi:[1,0]
	s_nop 0
	s_nop 0
	v_rcp_f32_e32 v151, v151
	s_nop 0
	s_nop 0
	v_lshlrev_b32_e32 v152, 16, v140
	v_and_b32_e32 v153, 0xffff0000, v140
	v_mul_f32_e32 v140, 0xbfb8aa3b, v18
	v_rcp_f32_e32 v150, v150
	s_nop 0
	v_exp_f32_e32 v144, v140
	v_mul_f32_e32 v140, 0xbfb8aa3b, v19
	v_pk_fma_f32 v[150:151], v[150:151], v[138:139], v[152:153]
	v_lshlrev_b32_e32 v138, 16, v145
	v_and_b32_e32 v139, 0xffff0000, v145
	v_exp_f32_e32 v145, v140
	s_nop 0
	v_pk_add_f32 v[144:145], v[144:145], 1.0 op_sel_hi:[1,0]
	s_nop 0
	s_nop 0
	v_rcp_f32_e32 v145, v145
	s_nop 0
	s_nop 0
	v_rcp_f32_e32 v144, v144
	s_nop 0
	v_lshlrev_b32_e32 v140, 16, v141
	v_and_b32_e32 v141, 0xffff0000, v141
	v_pk_fma_f32 v[144:145], v[144:145], v[138:139], v[140:141]
	v_cvt_pk_bf16_f32 v138, v148, v149
	v_cvt_pk_bf16_f32 v139, v142, v143
	v_cvt_pk_bf16_f32 v140, v150, v151
	v_cvt_pk_bf16_f32 v141, v144, v145
	global_store_dwordx4 v[146:147], v[138:141], off
	s_nop 1
	v_lshlrev_b32_e32 v138, 16, v134
	v_and_b32_e32 v139, 0xffff0000, v134
	v_mul_f32_e32 v134, 0xbfb8aa3b, v4
	v_exp_f32_e32 v140, v134
	v_mul_f32_e32 v134, 0xbfb8aa3b, v5
	v_exp_f32_e32 v141, v134
	s_nop 0
	v_pk_add_f32 v[140:141], v[140:141], 1.0 op_sel_hi:[1,0]
	s_nop 0
	s_nop 0
	v_rcp_f32_e32 v141, v141
	s_nop 0
	s_nop 0
	v_rcp_f32_e32 v140, v140
	s_nop 0
	v_lshlrev_b32_e32 v142, 16, v130
	v_and_b32_e32 v143, 0xffff0000, v130
	v_mul_f32_e32 v130, 0xbfb8aa3b, v6
	v_pk_fma_f32 v[138:139], v[140:141], v[138:139], v[142:143]
	v_exp_f32_e32 v140, v130
	v_mul_f32_e32 v130, 0xbfb8aa3b, v7
	v_exp_f32_e32 v141, v130
	v_lshlrev_b32_e32 v134, 16, v135
	v_and_b32_e32 v135, 0xffff0000, v135
	v_pk_add_f32 v[140:141], v[140:141], 1.0 op_sel_hi:[1,0]
	s_nop 0
	s_nop 0
	v_rcp_f32_e32 v141, v141
	s_nop 0
	s_nop 0
	v_rcp_f32_e32 v140, v140
	s_nop 0
	v_lshlrev_b32_e32 v130, 16, v131
	v_and_b32_e32 v131, 0xffff0000, v131
	v_pk_fma_f32 v[134:135], v[140:141], v[134:135], v[130:131]
	v_lshlrev_b32_e32 v130, 16, v136
	v_and_b32_e32 v131, 0xffff0000, v136
	v_mul_f32_e32 v136, 0xbfb8aa3b, v0
	v_exp_f32_e32 v140, v136
	v_mul_f32_e32 v136, 0xbfb8aa3b, v1
	v_exp_f32_e32 v141, v136
	s_nop 0
	v_pk_add_f32 v[140:141], v[140:141], 1.0 op_sel_hi:[1,0]
	s_nop 0
	s_nop 0
	v_rcp_f32_e32 v141, v141
	s_nop 0
	s_nop 0
	v_lshlrev_b32_e32 v142, 16, v132
	v_and_b32_e32 v143, 0xffff0000, v132
	v_mul_f32_e32 v132, 0xbfb8aa3b, v2
	v_rcp_f32_e32 v140, v140
	s_nop 0
	v_exp_f32_e32 v136, v132
	v_mul_f32_e32 v132, 0xbfb8aa3b, v3
	v_pk_fma_f32 v[140:141], v[140:141], v[130:131], v[142:143]
	v_lshlrev_b32_e32 v130, 16, v137
	v_and_b32_e32 v131, 0xffff0000, v137
	v_exp_f32_e32 v137, v132
	s_nop 0
	v_pk_add_f32 v[136:137], v[136:137], 1.0 op_sel_hi:[1,0]
	s_nop 0
	s_nop 0
	v_rcp_f32_e32 v137, v137
	s_nop 0
	s_nop 0
	v_rcp_f32_e32 v136, v136
	s_nop 0
	v_lshlrev_b32_e32 v132, 16, v133
	v_and_b32_e32 v133, 0xffff0000, v133
	v_pk_fma_f32 v[136:137], v[136:137], v[130:131], v[132:133]
	v_cvt_pk_bf16_f32 v130, v138, v139
	v_cvt_pk_bf16_f32 v131, v134, v135
	v_cvt_pk_bf16_f32 v132, v140, v141
	v_cvt_pk_bf16_f32 v133, v136, v137
	global_store_dwordx4 v[146:147], v[130:133], off offset:256
